# entry kernarg pointer loads issued together (one wait); XCC-id check: 4 loads in one round trip
# speedup vs baseline: 1.0160x; 1.0160x over previous
; #define LAS __attribute__((address_space(3)))
; __device__ __forceinline__ unsigned pk2(float lo, float hi) { return pg8::cvt_pk_bf16(lo, hi); }
; __device__ __forceinline__ void tr_item(const float* W, int ldw, int K, int k0, int sc0, bf16* WT, int dr0, const float* gain, float cs, LAS float* scr, int lane) {
; #pragma unroll 16
;     for (int i = 0; i < 32; ++i) { const int kk = 2 * i + (lane >> 5); const float g = gain ? gain[k0 + kk] * cs : cs;
;         scr[kk * 33 + (lane & 31)] = W[(size_t)(k0 + kk) * ldw + sc0 + (lane & 31)] * g; }
;     asm volatile("s_waitcnt lgkmcnt(0)" ::: "memory");
;     const int c = lane & 7;
; #pragma unroll
;     for (int j = 0; j < 4; ++j) { const int n = (lane >> 3) + 8 * j; const LAS float* s = scr + (8 * c) * 33 + n;
;         u32x4 o; o.x = pk2(s[0 * 33], s[1 * 33]); o.y = pk2(s[2 * 33], s[3 * 33]); o.z = pk2(s[4 * 33], s[5 * 33]); o.w = pk2(s[6 * 33], s[7 * 33]);
;         *(u32x4*)(WT + (size_t)(dr0 + n) * K + k0 + 8 * c) = o; }
.LBB0_14:
	s_load_dwordx4 s[16:19], s[0:1], 0xa0
	s_load_dwordx2 s[8:9], s[0:1], 0x0
	s_load_dwordx2 s[30:31], s[0:1], 0x8
	s_load_dwordx2 s[6:7], s[0:1], 0x10
	s_load_dwordx2 s[10:11], s[0:1], 0x18
	s_load_dwordx2 s[14:15], s[0:1], 0x20
	s_load_dwordx2 s[12:13], s[0:1], 0x30
	s_load_dwordx2 s[34:35], s[0:1], 0x38
	s_load_dwordx2 s[36:37], s[0:1], 0x40
	s_load_dwordx2 s[52:53], s[0:1], 0x48
	s_load_dwordx2 s[58:59], s[0:1], 0x50
	s_load_dwordx2 s[38:39], s[0:1], 0x58
	s_load_dwordx2 s[40:41], s[0:1], 0x60
	s_load_dwordx2 s[4:5], s[0:1], 0x68
	s_load_dwordx2 s[54:55], s[0:1], 0x70
	s_load_dwordx2 s[48:49], s[0:1], 0x78
	s_load_dwordx2 s[42:43], s[0:1], 0x80
	s_load_dwordx2 s[56:57], s[0:1], 0x88
	s_load_dwordx2 s[46:47], s[0:1], 0x90
	s_load_dwordx2 s[50:51], s[0:1], 0x98
	s_mov_b32 s44, s20
	s_mov_b32 s60, s2
	s_lshr_b32 s74, s72, 6
	v_mbcnt_hi_u32_b32 v212, -1, v0
	s_lshl_b32 s3, s60, 3
	s_add_i32 s26, s3, s74
	s_lshl_b32 s28, s44, 3
	s_mov_b32 s45, 0
	v_mov_b32_e32 v32, v212
	s_waitcnt lgkmcnt(0)
	s_mov_b64 s[24:25], s[18:19]
	s_cmpk_gt_i32 s26, 0x1f7f
	v_ashrrev_i32_e32 v0, 3, v32
	s_cbranch_scc1 .LBB0_186
	v_lshlrev_b32_e32 v1, 2, v32
	v_and_b32_e32 v44, 0x7c, v1
	v_lshlrev_b32_e32 v1, 3, v32
	s_lshl_b32 s27, s74, 14
	v_mov_b32_e32 v45, 0
	v_and_b32_e32 v1, 56, v1
	s_add_i32 s3, s27, 0
	v_lshlrev_b32_e32 v6, 1, v1
	v_mov_b32_e32 v7, v45
	v_lshl_add_u64 v[4:5], s[46:47], 0, v[44:45]
	v_lshl_add_u64 v[26:27], s[24:25], 0, v[6:7]
	s_mov_b64 s[46:47], 0x1c00000
	s_cmp_lg_u64 s[42:43], 0
	v_lshl_add_u64 v[6:7], v[26:27], 0, s[46:47]
	s_cselect_b64 s[46:47], -1, 0
	s_mov_b64 s[50:51], 0x1100000
	v_lshl_add_u64 v[10:11], s[48:49], 0, v[44:45]
	s_mov_b64 s[48:49], 0x1000000
	s_cmp_lg_u64 s[40:41], 0
	v_lshl_add_u64 v[8:9], v[26:27], 0, s[50:51]
	v_lshl_add_u64 v[12:13], v[26:27], 0, s[48:49]
	s_cselect_b64 s[48:49], -1, 0
	s_mov_b64 s[50:51], 0xe00000
	s_cmp_lg_u64 s[38:39], 0
	v_ashrrev_i32_e32 v2, 5, v32
	v_lshl_add_u64 v[14:15], v[26:27], 0, s[50:51]
	s_cselect_b64 s[50:51], -1, 0
	v_lshl_add_u64 v[22:23], s[52:53], 0, v[44:45]
	s_mov_b64 s[52:53], 0x900400
	s_cmp_lg_u64 s[6:7], 0
	s_movk_i32 s29, 0x84
	v_mul_u32_u24_e32 v3, 0x84, v1
	v_lshlrev_b32_e32 v1, 2, v0
	s_mov_b64 s[62:63], 0xd00000
	v_lshl_add_u64 v[24:25], v[26:27], 0, s[52:53]
	s_cselect_b64 s[52:53], -1, 0
	v_ashrrev_i32_e32 v29, 31, v2
	v_mov_b32_e32 v28, v2
	v_lshl_add_u64 v[40:41], s[4:5], 0, v[44:45]
	s_lshl_b32 s4, s60, 5
	s_lshl_b32 s5, s74, 2
	v_add_u32_e32 v73, s3, v44
	v_add3_u32 v75, s3, v3, v1
	v_lshl_add_u64 v[16:17], v[26:27], 0, s[62:63]
	v_lshl_add_u64 v[18:19], s[58:59], 0, v[44:45]
	s_mov_b64 s[58:59], 0xb00000
	s_lshl_b32 s3, s60, 4
	s_lshl_b32 s21, s74, 1
	v_mul_lo_u32 v118, v2, s29
	v_lshlrev_b64 v[34:35], 2, v[28:29]
	v_lshl_add_u64 v[36:37], s[54:55], 0, v[44:45]
	s_movk_i32 s54, 0xa008
	s_add_i32 s62, s4, s5
	s_mov_b32 s4, 0xffff5008
	v_lshl_add_u64 v[20:21], v[26:27], 0, s[58:59]
	s_mov_b64 s[58:59], 0x100000
	s_add_i32 s3, s3, s21
	v_add_u32_e32 v1, s27, v118
	s_lshl_b32 s27, s60, 8
	s_lshl_b32 s29, s74, 5
	v_lshl_add_u64 v[38:39], s[40:41], 0, v[34:35]
	s_mov_b32 s55, -1
	v_lshl_add_u64 v[42:43], s[38:39], 0, v[34:35]
	s_mov_b32 s5, -1
	v_add_u32_e32 v114, 8, v0
	v_add_u32_e32 v115, 16, v0
	v_add_u32_e32 v116, 24, v0
	v_lshl_add_u64 v[26:27], v[26:27], 0, s[58:59]
	v_add_u32_e32 v117, 0xffffcc00, v2
	s_lshl_b32 s21, s44, 4
	v_add_u32_e32 v119, 0x108, v118
	v_add_u32_e32 v120, 0x210, v118
	v_add_u32_e32 v121, 0x318, v118
	v_add_u32_e32 v122, 0x420, v118
	v_add_u32_e32 v123, 0x528, v118
	v_add_u32_e32 v124, 0x630, v118
	v_add3_u32 v125, v1, v44, 0
	v_lshl_add_u64 v[30:31], s[56:57], 0, v[44:45]
	s_add_i32 s27, s27, s29
	s_lshl_b32 s29, s44, 8
	v_lshl_add_u64 v[38:39], v[38:39], 0, s[54:55]
	s_lshl_b32 s63, s44, 5
	v_lshl_add_u64 v[42:43], v[42:43], 0, s[4:5]
	v_lshl_add_u64 v[44:45], s[10:11], 0, v[44:45]
	s_mov_b32 s64, 0x7fffffc2
	s_movk_i32 s65, 0x1600
	s_movk_i32 s66, 0x5800
	s_mov_b64 s[54:55], 0x80
	s_movk_i32 s67, 0x4020
	s_mov_b32 s68, s3
	s_mov_b32 s69, 0
	s_mov_b32 s70, s26
	v_add_u32_e32 v126, 0x738, v118
	v_add_u32_e32 v127, 0x840, v118
	v_add_u32_e32 v128, 0x948, v118
	v_add_u32_e32 v129, 0xa50, v118
	v_add_u32_e32 v130, 0xb58, v118
	v_add_u32_e32 v131, 0xc60, v118
	v_add_u32_e32 v132, 0xd68, v118
	v_add_u32_e32 v133, 0xe70, v118
	v_add_u32_e32 v134, 0xf78, v118
	v_add_u32_e32 v135, 0x1080, v118
	v_add_u32_e32 v136, 0x1188, v118
	v_add_u32_e32 v137, 0x1290, v118
	v_add_u32_e32 v138, 0x1398, v118
	v_add_u32_e32 v139, 0x14a0, v118
	v_add_u32_e32 v140, 0x15a8, v118
	v_add_u32_e32 v141, 0x16b0, v118
	v_add_u32_e32 v142, 0x17b8, v118
	v_add_u32_e32 v143, 0x18c0, v118
	v_add_u32_e32 v144, 0x19c8, v118
	v_add_u32_e32 v145, 0x1ad0, v118
	v_add_u32_e32 v146, 0x1bd8, v118
	v_add_u32_e32 v147, 0x1ce0, v118
	v_add_u32_e32 v148, 0x1de8, v118
	v_add_u32_e32 v149, 0x1ef0, v118
	v_add_u32_e32 v150, 0x1ff8, v118
	v_add_u32_e32 v151, 0xffffe81e, v2
	v_add_u32_e32 v152, 0xffffe800, v2
	v_add_u32_e32 v153, 0xffffe81c, v2
	v_add_u32_e32 v154, 0xffffe81a, v2
	v_add_u32_e32 v155, 0xffffe818, v2
	v_add_u32_e32 v156, 0xffffe802, v2
	v_add_u32_e32 v157, 0xffffe816, v2
	v_add_u32_e32 v158, 0xffffe804, v2
	v_add_u32_e32 v159, 0xffffe814, v2
	v_add_u32_e32 v160, 0xffffe806, v2
	v_add_u32_e32 v161, 0xffffe812, v2
	v_add_u32_e32 v162, 0xffffe808, v2
	v_add_u32_e32 v163, 0xffffe810, v2
	v_add_u32_e32 v164, 0xffffe80a, v2
	v_add_u32_e32 v165, 0xffffe80e, v2
	v_add_u32_e32 v166, 0xffffe80c, v2
	v_add_u32_e32 v167, 0xffffd41e, v2
	v_add_u32_e32 v168, 0xffffd400, v2
	v_add_u32_e32 v169, 0xffffd41c, v2
	v_add_u32_e32 v170, 0xffffd41a, v2
	v_add_u32_e32 v171, 0xffffd418, v2
	v_add_u32_e32 v172, 0xffffd402, v2
	v_add_u32_e32 v173, 0xffffd416, v2
	v_add_u32_e32 v174, 0xffffd404, v2
	v_add_u32_e32 v175, 0xffffd414, v2
	v_add_u32_e32 v176, 0xffffd406, v2
	v_add_u32_e32 v177, 0xffffd412, v2
	v_add_u32_e32 v178, 0xffffd408, v2
	v_add_u32_e32 v179, 0xffffd410, v2
	v_add_u32_e32 v180, 0xffffd40a, v2
	v_add_u32_e32 v181, 0xffffd40e, v2
	v_add_u32_e32 v182, 0xffffd40c, v2
	v_add_u32_e32 v1, 2, v2
	v_add_u32_e32 v3, 6, v2
	v_add_u32_e32 v46, 4, v2
	v_add_u32_e32 v33, 10, v2
	v_add_u32_e32 v48, 8, v2
	v_add_u32_e32 v47, 14, v2
	v_add_u32_e32 v50, 12, v2
	v_add_u32_e32 v49, 18, v2
	v_add_u32_e32 v52, 16, v2
	v_add_u32_e32 v51, 22, v2
	v_add_u32_e32 v54, 20, v2
	v_add_u32_e32 v53, 26, v2
	v_add_u32_e32 v56, 24, v2
	v_add_u32_e32 v55, 30, v2
	v_add_u32_e32 v58, 28, v2
	v_add_u32_e32 v57, 34, v2
	v_add_u32_e32 v60, 32, v2
	v_add_u32_e32 v59, 38, v2
	v_add_u32_e32 v62, 36, v2
	v_add_u32_e32 v61, 42, v2
	v_add_u32_e32 v64, 40, v2
	v_add_u32_e32 v63, 46, v2
	v_add_u32_e32 v66, 44, v2
	v_add_u32_e32 v65, 50, v2
	v_add_u32_e32 v68, 48, v2
	v_add_u32_e32 v67, 54, v2
	v_add_u32_e32 v70, 52, v2
	v_add_u32_e32 v69, 58, v2
	v_add_u32_e32 v72, 56, v2
	v_add_u32_e32 v71, 62, v2
	v_add_u32_e32 v74, 60, v2
	s_branch .LBB0_18

; __device__ __forceinline__ int hw_lane() { int l = (int)__builtin_amdgcn_mbcnt_hi(~0u, __builtin_amdgcn_mbcnt_lo(~0u, 0u)); asm volatile("" : "+v"(l)); return l; }
; __device__ __forceinline__ gptr_t opq_ptr(const void* p) { gptr_t g = (gptr_t)p; asm volatile("" : "+s"(g)); return g; }
; __global__ void __launch_bounds__(NTHR, 2) hybrid_fwd(Args args) {
;     ...
;         if (wave == 0) { const int l_ = hw_lane(); const unsigned* xt = (const unsigned*)opq_ptr(args.ws) + 2048; const unsigned mine = __hip_atomic_load(xt + blk, __ATOMIC_RELAXED, __HIP_MEMORY_SCOPE_AGENT); int ok = (G % 8 == 0);
;             for (int b2 = l_; b2 < G; b2 += 64) { const unsigned o = __hip_atomic_load(xt + b2, __ATOMIC_RELAXED, __HIP_MEMORY_SCOPE_AGENT); if ((o == mine) != ((b2 & 7) == (blk & 7))) ok = 0; }
;             ok = __all(ok); if (l_ == 0) *flagw = ok; }
.LBB0_213:
	s_or_b64 exec, exec, s[6:7]
	v_cndmask_b32_e64 v0, 0, 1, s[22:23]
	s_ashr_i32 s3, s2, 31
	v_cmp_ne_u32_e64 s[4:5], 1, v0
	s_andn2_b64 vcc, exec, s[22:23]
	s_barrier
	s_cbranch_vccnz .LBB0_221
	s_and_b32 s6, s20, 7
	s_cmp_eq_u32 s6, 0
	s_cselect_b64 s[10:11], -1, 0
	v_mov_b32_e32 v0, v212
	s_mov_b64 s[6:7], s[18:19]
	s_lshl_b64 s[8:9], s[2:3], 2
	s_add_u32 s8, s6, s8
	s_addc_u32 s9, s7, s9
	v_mov_b32_e32 v1, 0x2000
	global_load_dword v4, v1, s[8:9] sc1
	v_cmp_gt_i32_e32 vcc, s20, v0
	s_and_saveexec_b64 s[14:15], vcc
	s_cbranch_execz .LBB0_218
	v_ashrrev_i32_e32 v1, 31, v0
	v_lshl_add_u64 v[2:3], v[0:1], 2, s[6:7]
	s_mov_b64 s[6:7], 0x2000
	v_cndmask_b32_e64 v5, 0, 1, s[10:11]
	v_lshl_add_u64 v[2:3], v[2:3], 0, s[6:7]
	s_mov_b64 s[22:23], 0
	s_mov_b64 s[24:25], 0x100
	v_mov_b32_e32 v1, v0
	s_cmp_eq_u32 s20, 0x100
	s_cbranch_scc0 .LBB0_216
	global_load_dword v6, v[2:3], off sc1
	global_load_dword v8, v[2:3], off offset:256 sc1
	global_load_dword v9, v[2:3], off offset:512 sc1
	global_load_dword v10, v[2:3], off offset:768 sc1
	v_bitop3_b32 v7, v1, 7, s2 bitop3:0x48
	v_cmp_ne_u32_e64 s[24:25], 0, v7
	s_waitcnt vmcnt(0)
	v_cmp_eq_u32_e64 s[8:9], v6, v4
	s_xor_b64 vcc, s[24:25], s[8:9]
	v_cmp_eq_u32_e64 s[8:9], v8, v4
	v_cndmask_b32_e32 v5, 0, v5, vcc
	s_xor_b64 vcc, s[24:25], s[8:9]
	v_cmp_eq_u32_e64 s[8:9], v9, v4
	v_cndmask_b32_e32 v5, 0, v5, vcc
	s_xor_b64 vcc, s[24:25], s[8:9]
	v_cmp_eq_u32_e64 s[8:9], v10, v4
	v_cndmask_b32_e32 v5, 0, v5, vcc
	s_xor_b64 vcc, s[24:25], s[8:9]
	s_nop 1
	v_cndmask_b32_e32 v5, 0, v5, vcc
	s_branch .Lxcc_join

; __global__ void __launch_bounds__(NTHR, 2) hybrid_fwd(Args args) {
;     ...
;             for (int b2 = l_; b2 < G; b2 += 64) { const unsigned o = __hip_atomic_load(xt + b2, __ATOMIC_RELAXED, __HIP_MEMORY_SCOPE_AGENT); if ((o == mine) != ((b2 & 7) == (blk & 7))) ok = 0; }
;             ok = __all(ok); if (l_ == 0) *flagw = ok; }
.Lxcc_join:
	s_or_b64 exec, exec, s[22:23]
	v_cmp_ne_u32_e32 vcc, 0, v5
	s_andn2_b64 s[6:7], s[10:11], exec
	s_and_b64 s[8:9], vcc, exec
	s_or_b64 s[10:11], s[6:7], s[8:9]
